# prologue hidden-state init: the 4 row pieces loaded together (was 4 serial load-wait-store steps); oddnorm: rotary table loads issued with the row loads
# baseline (speedup 1.0000x reference)
; #define GAS __attribute__((address_space(1)))
; __device__ __forceinline__ unsigned pk2(float lo, float hi) { f32x2v v = {lo, hi}; bf16x2v b = __builtin_convertvector(v, bf16x2v); return __builtin_bit_cast(unsigned, b); }
; #define GAS __attribute__((address_space(1)))
; DI float bflo(unsigned w) { return __uint_as_float(w << 16); }
; DI float bfhi(unsigned w) { return __uint_as_float(w & 0xffff0000u); }
; template <int MASK> DI float swz_xor(float v) { return __int_as_float(__builtin_amdgcn_ds_swizzle(__float_as_int(v), (MASK << 10) | 0x1f)); }
; DI float bf1(const bf16_t* p) { return __uint_as_float((unsigned)(*(GAS const bf16_t*)p) << 16); }
; DI void phase_oddnorm(const bf16_t* U2, const float* qn, const float* kvn, const float* cs, const float* sn, bf16_t* CQN, bf16_t* CKVN, bf16_t* K) {
;     ...
;     for (int row = gw; row < M; row += nw) {
;         const bf16_t* u = U2 + (size_t)row * 768; const int t = row % TT;
;         GAS const unsigned* uq = (GAS const unsigned*)(u + lane * 6); const unsigned w0 = uq[0], w1 = uq[1], w2 = uq[2];
;         float q[6] = {bflo(w0), bfhi(w0), bflo(w1), bfhi(w1), bflo(w2), bfhi(w2)};
;         float ss = 0.f;
; #pragma unroll
;         for (int e = 0; e < 6; ++e) ss += q[e] * q[e];
;         const float rq = rsqrtf(wave_sum(ss) * (1.f / 384) + EPS);
;         GAS unsigned* oq = (GAS unsigned*)(CQN + (size_t)row * 384 + lane * 6);
;         oq[0] = pk2(q[0] * rq * gq[0], q[1] * rq * gq[1]); oq[1] = pk2(q[2] * rq * gq[2], q[3] * rq * gq[3]); oq[2] = pk2(q[4] * rq * gq[4], q[5] * rq * gq[5]);
;         const u32x2 kw = *(GAS const u32x2*)(u + 384 + lane * 4);
;         float kv[4] = {bflo(kw.x), bfhi(kw.x), bflo(kw.y), bfhi(kw.y)};
;         float s2 = (kv[0] * kv[0] + kv[1] * kv[1]) + (kv[2] * kv[2] + kv[3] * kv[3]);
;         const float rk = rsqrtf(wave_sum(s2) * (1.f / 256) + EPS);
;         u32x2 ow; ow.x = pk2(kv[0] * rk * gk[0], kv[1] * rk * gk[1]); ow.y = pk2(kv[2] * rk * gk[2], kv[3] * rk * gk[3]);
;         *(GAS u32x2*)(CKVN + (size_t)row * 256 + lane * 4) = ow;
;         const float x = bf1(u + 640 + (lane & 31)); const float xp = swz_xor<16>(x);
;         const float c = cs[t * 16 + (lane & 15)], s = sn[t * 16 + (lane & 15)];
;         const float o = (lane & 16) ? (x * c + xp * s) : (x * c - xp * s);
;         const bf16_t ob = tobf(o);
;         if (lane < 32) {
.LBB0_99:
	v_mov_b64_e32 v[24:25], s[38:39]
	s_movk_i32 s10, 0x600
	v_mad_i64_i32 v[28:29], s[10:11], v8, s10, v[24:25]
	v_lshl_add_u64 v[24:25], v[28:29], 0, v[64:65]
	global_load_dwordx3 v[24:26], v[24:25], off
	v_lshl_add_u64 v[54:55], v[28:29], 0, v[58:59]
	global_load_dwordx2 v[54:55], v[54:55], off offset:768
	v_lshl_add_u64 v[56:57], v[28:29], 0, v[60:61]
	global_load_ushort v56, v[56:57], off offset:1280
	s_and_saveexec_b64 s[34:35], s[8:9]
	v_mul_hi_i32 v38, v8, s85
	v_lshrrev_b32_e32 v39, 31, v38
	v_ashrrev_i32_e32 v38, 11, v38
	v_add_u32_e32 v38, v38, v39
	v_mul_i32_i24_e32 v39, 0x1010, v38
	v_lshlrev_b32_e32 v40, 4, v39
	v_sub_u32_e32 v40, v22, v40
	v_ashrrev_i32_e32 v41, 31, v40
	v_readlane_b32 s10, v254, 26
	v_lshlrev_b64 v[40:41], 2, v[40:41]
	v_readlane_b32 s11, v254, 27
	s_nop 3
	v_lshl_add_u64 v[42:43], s[10:11], 0, v[40:41]
	v_readlane_b32 s10, v254, 24
	flat_load_dword v52, v[42:43]
	v_readlane_b32 s11, v254, 25
	s_nop 3
	v_lshl_add_u64 v[40:41], s[10:11], 0, v[40:41]
	flat_load_dword v53, v[40:41]
	s_mov_b64 exec, s[34:35]
	s_waitcnt vmcnt(0)
	v_lshlrev_b32_e32 v30, 16, v24
	v_and_b32_e32 v31, 0xffff0000, v24
	v_lshlrev_b32_e32 v24, 16, v25
	v_and_b32_e32 v25, 0xffff0000, v25
	v_lshlrev_b32_e32 v32, 16, v26
	v_and_b32_e32 v33, 0xffff0000, v26
	v_pk_mul_f32 v[26:27], v[30:31], v[30:31]
	v_pk_mul_f32 v[34:35], v[24:25], v[24:25]
	v_add_f32_e32 v9, v26, v27
	v_add_f32_e32 v9, v9, v34
	v_pk_mul_f32 v[36:37], v[32:33], v[32:33]
	v_add_f32_e32 v9, v35, v9
	v_add_f32_e32 v9, v36, v9
	v_add_f32_e32 v9, v37, v9
	s_waitcnt lgkmcnt(0)
	ds_swizzle_b32 v19, v9 offset:swizzle(SWAP,1)
	v_mad_i64_i32 v[34:35], s[10:11], v8, s66, v[12:13]
	s_waitcnt lgkmcnt(0)
	v_add_f32_e32 v9, v9, v19
	ds_swizzle_b32 v19, v9 offset:swizzle(SWAP,2)
	s_waitcnt lgkmcnt(0)
	v_add_f32_e32 v9, v9, v19
	ds_swizzle_b32 v19, v9 offset:swizzle(SWAP,4)
	s_waitcnt lgkmcnt(0)
	v_add_f32_e32 v9, v9, v19
	ds_swizzle_b32 v19, v9 offset:swizzle(SWAP,8)
	s_waitcnt lgkmcnt(0)
	v_add_f32_e32 v9, v9, v19
	ds_swizzle_b32 v19, v9 offset:swizzle(SWAP,16)
	s_waitcnt lgkmcnt(0)
	v_add_f32_e32 v9, v9, v19
	v_mov_b32_e32 v19, v9
	s_nop 1
	v_permlane32_swap_b32_e32 v9, v19
	v_add_f32_e32 v9, v9, v19
	v_fmamk_f32 v9, v9, 0x3b2aaaab, v156
	v_mul_f32_e32 v19, 0x4b800000, v9
	v_cmp_gt_f32_e32 vcc, s90, v9
	s_nop 1
	v_cndmask_b32_e32 v9, v9, v19, vcc
	v_rsq_f32_e32 v9, v9
	v_mov_b32_e32 v19, v65
	v_lshl_add_u64 v[36:37], v[28:29], 0, v[18:19]
	v_mul_f32_e32 v19, 0x45800000, v9
	v_cndmask_b32_e32 v26, v9, v19, vcc
	v_pk_mul_f32 v[30:31], v[26:27], v[30:31] op_sel_hi:[0,1]
	v_pk_mul_f32 v[24:25], v[26:27], v[24:25] op_sel_hi:[0,1]
	v_pk_mul_f32 v[26:27], v[26:27], v[32:33] op_sel_hi:[0,1]
	v_pk_mul_f32 v[30:31], v[0:1], v[30:31]
	v_pk_mul_f32 v[32:33], v[2:3], v[24:25]
	v_pk_mul_f32 v[26:27], v[10:11], v[26:27]
	v_cvt_pk_bf16_f32 v24, v30, v31
	v_cvt_pk_bf16_f32 v25, v32, v33
	v_cvt_pk_bf16_f32 v26, v26, v27
	global_store_dwordx3 v[34:35], v[24:26], off
	s_nop 1
	v_mov_b32_e32 v24, v54
	v_mov_b32_e32 v25, v55
	v_and_b32_e32 v27, 0xffff0000, v25
	v_lshlrev_b32_e32 v26, 16, v25
	v_lshlrev_b32_e32 v30, 16, v24
	v_and_b32_e32 v31, 0xffff0000, v24
	v_pk_mul_f32 v[24:25], v[26:27], v[26:27]
	v_pk_mul_f32 v[32:33], v[30:31], v[30:31]
	v_add_f32_e32 v9, v24, v25
	v_add_f32_e32 v19, v32, v33
	v_add_f32_e32 v9, v19, v9
	ds_swizzle_b32 v19, v9 offset:swizzle(SWAP,1)
	s_waitcnt lgkmcnt(0)
	v_add_f32_e32 v9, v9, v19
	ds_swizzle_b32 v19, v9 offset:swizzle(SWAP,2)
	s_waitcnt lgkmcnt(0)
	v_add_f32_e32 v9, v9, v19
	ds_swizzle_b32 v19, v9 offset:swizzle(SWAP,4)
	s_waitcnt lgkmcnt(0)
	v_add_f32_e32 v9, v9, v19
	ds_swizzle_b32 v19, v9 offset:swizzle(SWAP,8)
	s_waitcnt lgkmcnt(0)
	v_add_f32_e32 v19, v9, v19
	ds_swizzle_b32 v21, v19 offset:swizzle(SWAP,16)
	v_ashrrev_i32_e32 v9, 31, v8
	v_lshlrev_b64 v[24:25], 9, v[8:9]
	v_lshl_add_u64 v[24:25], v[14:15], 0, v[24:25]
	s_waitcnt lgkmcnt(0)
	v_add_f32_e32 v19, v19, v21
	v_mov_b32_e32 v21, v19
	s_nop 1
	v_permlane32_swap_b32_e32 v19, v21
	v_add_f32_e32 v19, v19, v21
	v_fmamk_f32 v19, v19, 0x3b800000, v156
	v_mul_f32_e32 v21, 0x4b800000, v19
	v_cmp_gt_f32_e32 vcc, s90, v19
	s_nop 1
	v_cndmask_b32_e32 v19, v19, v21, vcc
	v_rsq_f32_e32 v19, v19
	v_mov_b32_e32 v21, v65
	v_mul_f32_e32 v9, 0x45800000, v19
	v_cndmask_b32_e32 v32, v19, v9, vcc
	v_pk_mul_f32 v[30:31], v[32:33], v[30:31] op_sel_hi:[0,1]
	v_pk_mul_f32 v[26:27], v[32:33], v[26:27] op_sel_hi:[0,1]
	v_pk_mul_f32 v[30:31], v[4:5], v[30:31]
	v_pk_mul_f32 v[26:27], v[6:7], v[26:27]
	v_cvt_pk_bf16_f32 v30, v30, v31
	v_cvt_pk_bf16_f32 v31, v26, v27
	global_store_dwordx2 v[24:25], v[30:31], off
	v_mov_b32_e32 v9, v56
	v_lshlrev_b32_e32 v9, 16, v9
	ds_swizzle_b32 v19, v9 offset:swizzle(SWAP,16)
	s_and_saveexec_b64 s[34:35], s[8:9]
	s_cbranch_execz .LBB0_98
; template <int MASK> DI float swz_xor(float v) { return __int_as_float(__builtin_amdgcn_ds_swizzle(__float_as_int(v), (MASK << 10) | 0x1f)); }
; DI float bf1(const bf16_t* p) { return __uint_as_float((unsigned)(*(GAS const bf16_t*)p) << 16); }
; DI bf16_t tobf(float f) { return (bf16_t)(pk2(f, 0.f) & 0xffffu); }
; DI void phase_oddnorm(const bf16_t* U2, const float* qn, const float* kvn, const float* cs, const float* sn, bf16_t* CQN, bf16_t* CKVN, bf16_t* K) {
;     ...
;         const float x = bf1(u + 640 + (lane & 31)); const float xp = swz_xor<16>(x);
;         const float c = cs[t * 16 + (lane & 15)], s = sn[t * 16 + (lane & 15)];
;         const float o = (lane & 16) ? (x * c + xp * s) : (x * c - xp * s);
;         const bf16_t ob = tobf(o);
;         if (lane < 32) {
;             const int b_ = row / TT; bf16_t* kp = K + ((size_t)(b_ * 16) * TT + t) * 96 + 64 + lane;
; #pragma unroll
;             for (int h = 0; h < 16; ++h) kp[(size_t)h * TT * 96] = ob;
;         }
	v_mul_hi_i32 v21, v8, s85
	v_lshrrev_b32_e32 v23, 31, v21
	v_ashrrev_i32_e32 v21, 11, v21
	v_add_u32_e32 v21, v21, v23
	v_mul_i32_i24_e32 v23, 0x1010, v21
	v_lshlrev_b32_e32 v24, 4, v23
	v_sub_u32_e32 v24, v22, v24
	v_ashrrev_i32_e32 v25, 31, v24
	v_readlane_b32 s10, v254, 26
	v_lshlrev_b64 v[24:25], 2, v[24:25]
	v_readlane_b32 s11, v254, 27
	v_lshlrev_b32_e32 v21, 4, v21
	s_mov_b32 s12, 0x787000
	v_sub_u32_e32 v24, v8, v23
	v_mul_hi_i32_i24_e32 v27, 0x1010, v21
	v_mul_i32_i24_e32 v26, 0x1010, v21
	v_ashrrev_i32_e32 v25, 31, v24
	v_lshl_add_u64 v[24:25], v[26:27], 0, v[24:25]
	v_mad_u64_u32 v[26:27], s[10:11], v24, s71, v[16:17]
	v_mov_b32_e32 v24, v27
	s_mov_b32 s10, 0x6c6000
	v_add_co_u32_e32 v28, vcc, s10, v26
	v_mad_u64_u32 v[24:25], s[10:11], v25, s71, v[24:25]
	s_mov_b64 s[10:11], vcc
	v_add_co_u32_e32 v30, vcc, s12, v26
	s_mov_b32 s12, 0xc0000
	v_add_co_u32_e64 v32, s[12:13], s12, v26
	v_addc_co_u32_e64 v29, s[10:11], 0, v24, s[10:11]
	s_nop 0
	v_addc_co_u32_e64 v33, s[12:13], 0, v24, s[12:13]
	s_mov_b32 s12, 0x181000
	s_nop 0
	v_add_co_u32_e64 v34, s[12:13], s12, v26
	v_addc_co_u32_e32 v31, vcc, 0, v24, vcc
	s_nop 0
	v_addc_co_u32_e64 v35, s[12:13], 0, v24, s[12:13]
	s_mov_b32 s12, 0x242000
	s_nop 0
	v_add_co_u32_e64 v36, s[12:13], s12, v26
	s_mov_b32 s10, 0x848000
	s_nop 0
	v_addc_co_u32_e64 v37, s[12:13], 0, v24, s[12:13]
	s_mov_b32 s12, 0x303000
	s_nop 0
	v_add_co_u32_e64 v38, s[12:13], s12, v26
	v_add_co_u32_e32 v48, vcc, s10, v26
	s_nop 0
	v_addc_co_u32_e64 v39, s[12:13], 0, v24, s[12:13]
	s_mov_b32 s12, 0x3c3000
	s_nop 0
	v_add_co_u32_e64 v40, s[12:13], s12, v26
	v_addc_co_u32_e32 v49, vcc, 0, v24, vcc
	s_nop 0
	v_addc_co_u32_e64 v41, s[12:13], 0, v24, s[12:13]
	s_mov_b32 s12, 0x484000
	s_nop 0
	v_add_co_u32_e64 v42, s[12:13], s12, v26
	v_add_co_u32_e32 v50, vcc, 0x909000, v26
	s_nop 0
	v_addc_co_u32_e64 v43, s[12:13], 0, v24, s[12:13]
	s_mov_b32 s12, 0x545000
	s_nop 0
	v_add_co_u32_e64 v44, s[12:13], s12, v26
	v_mov_b32_e32 v27, v24
	s_nop 0
	v_addc_co_u32_e64 v45, s[12:13], 0, v24, s[12:13]
	s_mov_b32 s12, 0x606000
	s_nop 0
	v_add_co_u32_e64 v46, s[12:13], s12, v26
	v_addc_co_u32_e32 v51, vcc, 0, v24, vcc
	s_nop 0
	v_addc_co_u32_e64 v47, s[12:13], 0, v24, s[12:13]
	s_waitcnt lgkmcnt(0)
	v_mul_f32_e32 v19, v52, v19
	v_cndmask_b32_e64 v19, v19, -v19, s[6:7]
	v_fmac_f32_e32 v19, v53, v9
	v_cvt_pk_bf16_f32 v9, v19, s0
	flat_store_short v[26:27], v9 offset:128
	flat_store_short v[32:33], v9 offset:3200
	flat_store_short v[34:35], v9 offset:2176
	flat_store_short v[36:37], v9 offset:1152
	flat_store_short v[38:39], v9 offset:128
	flat_store_short v[40:41], v9 offset:3200
	flat_store_short v[42:43], v9 offset:2176
	flat_store_short v[44:45], v9 offset:1152
	flat_store_short v[46:47], v9 offset:128
	flat_store_short v[28:29], v9 offset:3200
	flat_store_short v[30:31], v9 offset:2176
	flat_store_short v[48:49], v9 offset:1152
	flat_store_short v[50:51], v9 offset:128
	v_add_co_u32_e32 v28, vcc, 0x9c9000, v26
	s_nop 1
	v_addc_co_u32_e32 v29, vcc, 0, v24, vcc
	flat_store_short v[28:29], v9 offset:3200
	v_add_co_u32_e32 v28, vcc, 0xa8a000, v26
	s_nop 1
	v_addc_co_u32_e32 v29, vcc, 0, v24, vcc
	v_add_co_u32_e32 v26, vcc, 0xb4b000, v26
	flat_store_short v[28:29], v9 offset:2176
	s_nop 0
	v_addc_co_u32_e32 v27, vcc, 0, v24, vcc
	flat_store_short v[26:27], v9 offset:1152
	s_branch .LBB0_98
